# v050_rmswait
# baseline (speedup 1.0000x reference)
; #define SCHED __builtin_amdgcn_sched_barrier(0)
; __device__ __forceinline__ void rmsnorm_rows(const float* __restrict__ xin, const float* __restrict__ g, u16* outb, float* outf,
;                                              int row_begin, int row_end, int row_step, const int tidx) {
;     ...
;   for (int row = row_begin; row < row_end; row += row_step) {
;     const float* xr = xin + (size_t)row * DM;
;     f32x4 v[16];
;     float ss = 0.f;
; #pragma unroll
;     for (int i = 0; i < 16; ++i) {
;       v[i] = *reinterpret_cast<const f32x4*>(xr + i * 256 + lane * 4);
;     }
;     SCHED;
; #pragma unroll
;     for (int i = 0; i < 16; ++i) ss += v[i][0] * v[i][0] + v[i][1] * v[i][1] + v[i][2] * v[i][2] + v[i][3] * v[i][3];
;     ss = wave_sum(ss);
.LBB0_224:
	v_lshl_add_u64 v[64:65], v[132:133], 0, v[162:163]
	v_add_co_u32_e32 v66, vcc, 0x37900000, v64
	s_nop 1
	v_addc_co_u32_e32 v67, vcc, 0, v65, vcc
	global_load_dwordx4 v[126:129], v[66:67], off
	global_load_dwordx4 v[122:125], v[66:67], off offset:1024
	global_load_dwordx4 v[118:121], v[66:67], off offset:2048
	global_load_dwordx4 v[110:113], v[66:67], off offset:3072
	v_add_co_u32_e32 v66, vcc, 0x37901000, v64
	s_nop 1
	v_addc_co_u32_e32 v67, vcc, 0, v65, vcc
	global_load_dwordx4 v[114:117], v[66:67], off
	global_load_dwordx4 v[106:109], v[66:67], off offset:1024
	global_load_dwordx4 v[102:105], v[66:67], off offset:2048
	global_load_dwordx4 v[92:95], v[66:67], off offset:3072
	v_add_co_u32_e32 v66, vcc, 0x37902000, v64
	s_nop 1
	v_addc_co_u32_e32 v67, vcc, 0, v65, vcc
	v_add_co_u32_e32 v64, vcc, 0x37903000, v64
	global_load_dwordx4 v[98:101], v[66:67], off
	global_load_dwordx4 v[88:91], v[66:67], off offset:1024
	global_load_dwordx4 v[84:87], v[66:67], off offset:2048
	global_load_dwordx4 v[76:79], v[66:67], off offset:3072
	v_addc_co_u32_e32 v65, vcc, 0, v65, vcc
	global_load_dwordx4 v[80:83], v[64:65], off
	global_load_dwordx4 v[72:75], v[64:65], off offset:1024
	global_load_dwordx4 v[68:71], v[64:65], off offset:2048
	s_nop 0
	global_load_dwordx4 v[64:67], v[64:65], off offset:3072
	s_waitcnt vmcnt(15)
	v_mul_f32_e32 v131, v127, v127
	s_waitcnt vmcnt(14)
	v_mul_f32_e32 v141, v123, v123
	v_fmac_f32_e32 v131, v126, v126
	v_fmac_f32_e32 v141, v122, v122
	v_fmac_f32_e32 v131, v128, v128
	v_fmac_f32_e32 v141, v124, v124
	v_fmac_f32_e32 v131, v129, v129
	v_fmac_f32_e32 v141, v125, v125
	v_add_f32_e32 v131, v131, v141
	s_waitcnt vmcnt(13)
	v_mul_f32_e32 v141, v119, v119
	v_fmac_f32_e32 v141, v118, v118
	v_fmac_f32_e32 v141, v120, v120
	v_fmac_f32_e32 v141, v121, v121
	v_add_f32_e32 v131, v131, v141
	s_waitcnt vmcnt(12)
	v_mul_f32_e32 v141, v111, v111
	v_fmac_f32_e32 v141, v110, v110
	v_fmac_f32_e32 v141, v112, v112
	v_fmac_f32_e32 v141, v113, v113
	v_add_f32_e32 v131, v131, v141
	s_waitcnt vmcnt(11)
	v_mul_f32_e32 v141, v115, v115
	v_fmac_f32_e32 v141, v114, v114
	v_fmac_f32_e32 v141, v116, v116
	v_fmac_f32_e32 v141, v117, v117
	v_add_f32_e32 v131, v131, v141
	s_waitcnt vmcnt(10)
	v_mul_f32_e32 v141, v107, v107
	v_fmac_f32_e32 v141, v106, v106
	v_fmac_f32_e32 v141, v108, v108
	v_fmac_f32_e32 v141, v109, v109
	v_add_f32_e32 v131, v131, v141
	s_waitcnt vmcnt(9)
	v_mul_f32_e32 v141, v103, v103
	v_fmac_f32_e32 v141, v102, v102
	v_fmac_f32_e32 v141, v104, v104
	v_fmac_f32_e32 v141, v105, v105
	v_add_f32_e32 v131, v131, v141
	s_waitcnt vmcnt(8)
	v_mul_f32_e32 v141, v93, v93
	v_fmac_f32_e32 v141, v92, v92
	v_fmac_f32_e32 v141, v94, v94
	v_fmac_f32_e32 v141, v95, v95
	v_add_f32_e32 v131, v131, v141
	s_waitcnt vmcnt(7)
	v_mul_f32_e32 v141, v99, v99
	v_fmac_f32_e32 v141, v98, v98
	v_fmac_f32_e32 v141, v100, v100
	v_fmac_f32_e32 v141, v101, v101
	v_add_f32_e32 v131, v131, v141
	s_waitcnt vmcnt(6)
	v_mul_f32_e32 v141, v89, v89
	v_fmac_f32_e32 v141, v88, v88
	v_fmac_f32_e32 v141, v90, v90
	v_fmac_f32_e32 v141, v91, v91
	v_add_f32_e32 v131, v131, v141
	s_waitcnt vmcnt(5)
	v_mul_f32_e32 v141, v85, v85
	v_fmac_f32_e32 v141, v84, v84
	v_fmac_f32_e32 v141, v86, v86
	v_fmac_f32_e32 v141, v87, v87
	v_add_f32_e32 v131, v131, v141
	s_waitcnt vmcnt(4)
	v_mul_f32_e32 v141, v77, v77
	s_waitcnt vmcnt(3)
	v_mov_b32_e32 v144, v81
	s_waitcnt vmcnt(2)
	v_mov_b32_e32 v145, v73
	v_fmac_f32_e32 v141, v76, v76
	v_mov_b32_e32 v142, v80
	v_mov_b32_e32 v143, v72
	v_pk_mul_f32 v[144:145], v[144:145], v[144:145]
	v_fmac_f32_e32 v141, v78, v78
	v_pk_fma_f32 v[142:143], v[142:143], v[142:143], v[144:145]
	v_mov_b32_e32 v144, v82
	v_mov_b32_e32 v145, v74
	v_fmac_f32_e32 v141, v79, v79
	v_pk_fma_f32 v[142:143], v[144:145], v[144:145], v[142:143]
	v_mov_b32_e32 v144, v83
	v_mov_b32_e32 v145, v75
	v_add_f32_e32 v131, v131, v141
	v_pk_fma_f32 v[142:143], v[144:145], v[144:145], v[142:143]
	s_waitcnt vmcnt(1)
	v_mov_b32_e32 v144, v69
	v_add_f32_e32 v131, v131, v142
	s_waitcnt vmcnt(0)
	v_mov_b32_e32 v145, v65
	v_add_f32_e32 v131, v131, v143
	v_mov_b32_e32 v142, v68
	v_mov_b32_e32 v143, v64
	v_pk_mul_f32 v[144:145], v[144:145], v[144:145]
	v_add_u32_e32 v130, s8, v130
	v_pk_fma_f32 v[142:143], v[142:143], v[142:143], v[144:145]
	v_mov_b32_e32 v144, v70
	v_mov_b32_e32 v145, v66
	v_pk_fma_f32 v[142:143], v[144:145], v[144:145], v[142:143]
	v_mov_b32_e32 v144, v71
	v_mov_b32_e32 v145, v67
	v_pk_fma_f32 v[142:143], v[144:145], v[144:145], v[142:143]
	v_lshl_add_u64 v[144:145], v[134:135], 0, v[162:163]
	v_add_f32_e32 v131, v131, v142
	v_add_f32_e32 v131, v131, v143
	ds_bpermute_b32 v141, v97, v131
	v_lshl_add_u64 v[132:133], v[132:133], 0, s[10:11]
	v_lshl_add_u64 v[134:135], v[134:135], 0, s[10:11]
	s_waitcnt lgkmcnt(0)
	v_add_f32_e32 v131, v131, v141
	ds_bpermute_b32 v141, v136, v131
	s_waitcnt lgkmcnt(0)
	v_add_f32_e32 v131, v131, v141
	ds_bpermute_b32 v141, v137, v131
	s_waitcnt lgkmcnt(0)
	v_add_f32_e32 v131, v131, v141
	ds_bpermute_b32 v141, v138, v131
	s_waitcnt lgkmcnt(0)
	v_add_f32_e32 v131, v131, v141
	ds_bpermute_b32 v141, v139, v131
	s_waitcnt lgkmcnt(0)
; __device__ __forceinline__ void rmsnorm_rows(const float* __restrict__ xin, const float* __restrict__ g, u16* outb, float* outf,
;                                              int row_begin, int row_end, int row_step, const int tidx) {
;     ...
;     ss = wave_sum(ss);
;     float rs = rsqrtf(ss * (1.f / DM) + 1e-6f);
; #pragma unroll
;     for (int i = 0; i < 16; ++i) {
;       f32x4 o = v[i] * rs * ggv[i];
;       if (outb) {
;         u32x2 pk;
;         pk.x = pack2(o[0], o[1]);
;         pk.y = pack2(o[2], o[3]);
;         *reinterpret_cast<u32x2*>(outb + (size_t)row * DM + i * 256 + lane * 4) = pk;
;       } else {
;         *reinterpret_cast<f32x4*>(outf + (size_t)row * DM + i * 256 + lane * 4) = o;
;       }
;     }
	v_add_f32_e32 v131, v131, v141
	ds_bpermute_b32 v141, v140, v131
	s_waitcnt lgkmcnt(0)
	v_add_f32_e32 v131, v131, v141
	v_fmamk_f32 v131, v131, 0x39800000, v211
	v_cmp_gt_f32_e32 vcc, s1, v131
	v_mul_f32_e32 v141, 0x4b800000, v131
	s_nop 0
	v_cndmask_b32_e32 v131, v131, v141, vcc
	v_rsq_f32_e32 v131, v131
	s_nop 0
	v_mul_f32_e32 v141, 0x45800000, v131
	v_cndmask_b32_e32 v142, v131, v141, vcc
	v_pk_mul_f32 v[110:111], v[110:111], v[142:143] op_sel_hi:[1,0]
	v_pk_mul_f32 v[112:113], v[112:113], v[142:143] op_sel_hi:[1,0]
	v_pk_mul_f32 v[110:111], v[12:13], v[110:111]
	v_pk_mul_f32 v[112:113], v[14:15], v[112:113]
	global_store_dwordx4 v[144:145], v[110:113], off offset:3072
	v_pk_mul_f32 v[76:77], v[76:77], v[142:143] op_sel_hi:[1,0]
	v_pk_mul_f32 v[78:79], v[78:79], v[142:143] op_sel_hi:[1,0]
	v_pk_mul_f32 v[110:111], v[114:115], v[142:143] op_sel_hi:[1,0]
	v_add_co_u32_e32 v114, vcc, s56, v144
	v_pk_mul_f32 v[112:113], v[116:117], v[142:143] op_sel_hi:[1,0]
	s_nop 0
	v_addc_co_u32_e32 v115, vcc, 0, v145, vcc
	v_add_co_u32_e32 v116, vcc, s51, v144
	v_pk_mul_f32 v[78:79], v[46:47], v[78:79]
	s_nop 0
	v_addc_co_u32_e32 v117, vcc, 0, v145, vcc
	v_pk_mul_f32 v[76:77], v[44:45], v[76:77]
	v_pk_mul_f32 v[92:93], v[92:93], v[142:143] op_sel_hi:[1,0]
	v_pk_mul_f32 v[94:95], v[94:95], v[142:143] op_sel_hi:[1,0]
	global_store_dwordx4 v[116:117], v[76:79], off offset:3072
	v_pk_mul_f32 v[94:95], v[30:31], v[94:95]
	v_pk_mul_f32 v[92:93], v[28:29], v[92:93]
	v_pk_mul_f32 v[76:77], v[80:81], v[142:143] op_sel_hi:[1,0]
	v_add_co_u32_e32 v80, vcc, s14, v144
	v_pk_mul_f32 v[126:127], v[126:127], v[142:143] op_sel_hi:[1,0]
	s_nop 0
	v_addc_co_u32_e32 v81, vcc, 0, v145, vcc
	v_pk_mul_f32 v[128:129], v[128:129], v[142:143] op_sel_hi:[1,0]
	v_pk_mul_f32 v[122:123], v[122:123], v[142:143] op_sel_hi:[1,0]
	v_pk_mul_f32 v[124:125], v[124:125], v[142:143] op_sel_hi:[1,0]
	v_pk_mul_f32 v[118:119], v[118:119], v[142:143] op_sel_hi:[1,0]
	v_pk_mul_f32 v[120:121], v[120:121], v[142:143] op_sel_hi:[1,0]
	v_pk_mul_f32 v[106:107], v[106:107], v[142:143] op_sel_hi:[1,0]
	v_pk_mul_f32 v[108:109], v[108:109], v[142:143] op_sel_hi:[1,0]
	v_pk_mul_f32 v[102:103], v[102:103], v[142:143] op_sel_hi:[1,0]
	v_pk_mul_f32 v[104:105], v[104:105], v[142:143] op_sel_hi:[1,0]
	global_store_dwordx4 v[114:115], v[92:95], off offset:3072
	v_pk_mul_f32 v[88:89], v[88:89], v[142:143] op_sel_hi:[1,0]
	v_pk_mul_f32 v[90:91], v[90:91], v[142:143] op_sel_hi:[1,0]
	v_pk_mul_f32 v[92:93], v[98:99], v[142:143] op_sel_hi:[1,0]
	v_pk_mul_f32 v[94:95], v[100:101], v[142:143] op_sel_hi:[1,0]
	v_pk_mul_f32 v[84:85], v[84:85], v[142:143] op_sel_hi:[1,0]
	v_pk_mul_f32 v[86:87], v[86:87], v[142:143] op_sel_hi:[1,0]
	v_pk_mul_f32 v[78:79], v[82:83], v[142:143] op_sel_hi:[1,0]
	v_pk_mul_f32 v[72:73], v[72:73], v[142:143] op_sel_hi:[1,0]
	v_pk_mul_f32 v[74:75], v[74:75], v[142:143] op_sel_hi:[1,0]
	v_pk_mul_f32 v[68:69], v[68:69], v[142:143] op_sel_hi:[1,0]
	v_pk_mul_f32 v[70:71], v[70:71], v[142:143] op_sel_hi:[1,0]
	v_pk_mul_f32 v[64:65], v[64:65], v[142:143] op_sel_hi:[1,0]
	v_pk_mul_f32 v[66:67], v[66:67], v[142:143] op_sel_hi:[1,0]
	v_cmp_lt_i32_e32 vcc, s16, v130
	v_pk_mul_f32 v[128:129], v[2:3], v[128:129]
	v_pk_mul_f32 v[126:127], v[0:1], v[126:127]
	v_pk_mul_f32 v[124:125], v[6:7], v[124:125]
	v_pk_mul_f32 v[122:123], v[4:5], v[122:123]
	v_pk_mul_f32 v[120:121], v[10:11], v[120:121]
	v_pk_mul_f32 v[118:119], v[8:9], v[118:119]
	v_pk_mul_f32 v[112:113], v[18:19], v[112:113]
	v_pk_mul_f32 v[110:111], v[16:17], v[110:111]
	v_pk_mul_f32 v[108:109], v[22:23], v[108:109]
	v_pk_mul_f32 v[106:107], v[20:21], v[106:107]
	v_pk_mul_f32 v[104:105], v[26:27], v[104:105]
	v_pk_mul_f32 v[102:103], v[24:25], v[102:103]
	v_pk_mul_f32 v[94:95], v[34:35], v[94:95]
	v_pk_mul_f32 v[92:93], v[32:33], v[92:93]
	v_pk_mul_f32 v[90:91], v[38:39], v[90:91]
	v_pk_mul_f32 v[88:89], v[36:37], v[88:89]
	v_pk_mul_f32 v[86:87], v[42:43], v[86:87]
	v_pk_mul_f32 v[84:85], v[40:41], v[84:85]
	v_pk_mul_f32 v[78:79], v[50:51], v[78:79]
	v_pk_mul_f32 v[76:77], v[48:49], v[76:77]
	v_pk_mul_f32 v[74:75], v[54:55], v[74:75]
	v_pk_mul_f32 v[72:73], v[52:53], v[72:73]
	v_pk_mul_f32 v[70:71], v[58:59], v[70:71]
	v_pk_mul_f32 v[68:69], v[56:57], v[68:69]
	v_pk_mul_f32 v[66:67], v[62:63], v[66:67]
	v_pk_mul_f32 v[64:65], v[60:61], v[64:65]
	s_or_b64 s[12:13], vcc, s[12:13]
	global_store_dwordx4 v[144:145], v[126:129], off
	global_store_dwordx4 v[144:145], v[122:125], off offset:1024
	global_store_dwordx4 v[144:145], v[118:121], off offset:2048
	global_store_dwordx4 v[116:117], v[110:113], off offset:-4096
	global_store_dwordx4 v[114:115], v[106:109], off offset:1024
	global_store_dwordx4 v[114:115], v[102:105], off offset:2048
	global_store_dwordx4 v[116:117], v[92:95], off
	global_store_dwordx4 v[116:117], v[88:91], off offset:1024
	global_store_dwordx4 v[116:117], v[84:87], off offset:2048
	global_store_dwordx4 v[80:81], v[76:79], off
	global_store_dwordx4 v[80:81], v[72:75], off offset:1024
	global_store_dwordx4 v[80:81], v[68:71], off offset:2048
	global_store_dwordx4 v[80:81], v[64:67], off offset:3072
	s_andn2_b64 exec, exec, s[12:13]
	s_cbranch_execnz .LBB0_224

; #define SCHED __builtin_amdgcn_sched_barrier(0)
; __device__ __forceinline__ void rmsnorm_rows(const float* __restrict__ xin, const float* __restrict__ g, u16* outb, float* outf,
;                                              int row_begin, int row_end, int row_step, const int tidx) {
;     ...
;   for (int row = row_begin; row < row_end; row += row_step) {
;     const float* xr = xin + (size_t)row * DM;
;     f32x4 v[16];
;     float ss = 0.f;
; #pragma unroll
;     for (int i = 0; i < 16; ++i) {
;       v[i] = *reinterpret_cast<const f32x4*>(xr + i * 256 + lane * 4);
;     }
;     SCHED;
; #pragma unroll
;     for (int i = 0; i < 16; ++i) ss += v[i][0] * v[i][0] + v[i][1] * v[i][1] + v[i][2] * v[i][2] + v[i][3] * v[i][3];
;     ss = wave_sum(ss);
.LBB0_229:
	v_lshl_add_u64 v[64:65], s[86:87], 0, v[132:133]
	v_add_co_u32_e32 v66, vcc, 0x2f900000, v64
	s_nop 1
	v_addc_co_u32_e32 v67, vcc, 0, v65, vcc
	global_load_dwordx4 v[126:129], v[66:67], off
	global_load_dwordx4 v[122:125], v[66:67], off offset:1024
	global_load_dwordx4 v[118:121], v[66:67], off offset:2048
	global_load_dwordx4 v[110:113], v[66:67], off offset:3072
	v_add_co_u32_e32 v66, vcc, 0x2f901000, v64
	s_nop 1
	v_addc_co_u32_e32 v67, vcc, 0, v65, vcc
	global_load_dwordx4 v[114:117], v[66:67], off
	global_load_dwordx4 v[106:109], v[66:67], off offset:1024
	global_load_dwordx4 v[102:105], v[66:67], off offset:2048
	global_load_dwordx4 v[92:95], v[66:67], off offset:3072
	v_add_co_u32_e32 v66, vcc, 0x2f902000, v64
	s_nop 1
	v_addc_co_u32_e32 v67, vcc, 0, v65, vcc
	v_add_co_u32_e32 v64, vcc, 0x2f903000, v64
	global_load_dwordx4 v[98:101], v[66:67], off
	global_load_dwordx4 v[88:91], v[66:67], off offset:1024
	global_load_dwordx4 v[84:87], v[66:67], off offset:2048
	global_load_dwordx4 v[76:79], v[66:67], off offset:3072
	v_addc_co_u32_e32 v65, vcc, 0, v65, vcc
	global_load_dwordx4 v[80:83], v[64:65], off
	global_load_dwordx4 v[72:75], v[64:65], off offset:1024
	global_load_dwordx4 v[68:71], v[64:65], off offset:2048
	s_nop 0
	global_load_dwordx4 v[64:67], v[64:65], off offset:3072
	s_waitcnt vmcnt(15)
	v_mul_f32_e32 v131, v127, v127
	s_waitcnt vmcnt(14)
	v_mul_f32_e32 v141, v123, v123
	v_fmac_f32_e32 v131, v126, v126
	v_fmac_f32_e32 v141, v122, v122
	v_fmac_f32_e32 v131, v128, v128
	v_fmac_f32_e32 v141, v124, v124
	v_fmac_f32_e32 v131, v129, v129
	v_fmac_f32_e32 v141, v125, v125
	v_add_f32_e32 v131, v131, v141
	s_waitcnt vmcnt(13)
	v_mul_f32_e32 v141, v119, v119
	v_fmac_f32_e32 v141, v118, v118
	v_fmac_f32_e32 v141, v120, v120
	v_fmac_f32_e32 v141, v121, v121
	v_add_f32_e32 v131, v131, v141
	s_waitcnt vmcnt(12)
	v_mul_f32_e32 v141, v111, v111
	v_fmac_f32_e32 v141, v110, v110
	v_fmac_f32_e32 v141, v112, v112
	v_fmac_f32_e32 v141, v113, v113
	v_add_f32_e32 v131, v131, v141
	s_waitcnt vmcnt(11)
	v_mul_f32_e32 v141, v115, v115
	v_fmac_f32_e32 v141, v114, v114
	v_fmac_f32_e32 v141, v116, v116
	v_fmac_f32_e32 v141, v117, v117
	v_add_f32_e32 v131, v131, v141
	s_waitcnt vmcnt(10)
	v_mul_f32_e32 v141, v107, v107
	v_fmac_f32_e32 v141, v106, v106
	v_fmac_f32_e32 v141, v108, v108
	v_fmac_f32_e32 v141, v109, v109
	v_add_f32_e32 v131, v131, v141
	s_waitcnt vmcnt(9)
	v_mul_f32_e32 v141, v103, v103
	v_fmac_f32_e32 v141, v102, v102
	v_fmac_f32_e32 v141, v104, v104
	v_fmac_f32_e32 v141, v105, v105
	v_add_f32_e32 v131, v131, v141
	s_waitcnt vmcnt(8)
	v_mul_f32_e32 v141, v93, v93
	v_fmac_f32_e32 v141, v92, v92
	v_fmac_f32_e32 v141, v94, v94
	v_fmac_f32_e32 v141, v95, v95
	v_add_f32_e32 v131, v131, v141
	s_waitcnt vmcnt(7)
	v_mul_f32_e32 v141, v99, v99
	v_fmac_f32_e32 v141, v98, v98
	v_fmac_f32_e32 v141, v100, v100
	v_fmac_f32_e32 v141, v101, v101
	v_add_f32_e32 v131, v131, v141
	s_waitcnt vmcnt(6)
	v_mul_f32_e32 v141, v89, v89
	v_fmac_f32_e32 v141, v88, v88
	v_fmac_f32_e32 v141, v90, v90
	v_fmac_f32_e32 v141, v91, v91
	v_add_f32_e32 v131, v131, v141
	s_waitcnt vmcnt(5)
	v_mul_f32_e32 v141, v85, v85
	v_fmac_f32_e32 v141, v84, v84
	v_fmac_f32_e32 v141, v86, v86
	v_fmac_f32_e32 v141, v87, v87
	v_add_f32_e32 v131, v131, v141
	s_waitcnt vmcnt(4)
	v_mul_f32_e32 v141, v77, v77
	s_waitcnt vmcnt(3)
	v_mov_b32_e32 v144, v81
	s_waitcnt vmcnt(2)
	v_mov_b32_e32 v145, v73
	v_fmac_f32_e32 v141, v76, v76
	v_mov_b32_e32 v142, v80
	v_mov_b32_e32 v143, v72
	v_pk_mul_f32 v[144:145], v[144:145], v[144:145]
	v_fmac_f32_e32 v141, v78, v78
	v_pk_fma_f32 v[142:143], v[142:143], v[142:143], v[144:145]
	v_mov_b32_e32 v144, v82
	v_mov_b32_e32 v145, v74
	v_fmac_f32_e32 v141, v79, v79
	v_pk_fma_f32 v[142:143], v[144:145], v[144:145], v[142:143]
	v_mov_b32_e32 v144, v83
	v_mov_b32_e32 v145, v75
	v_add_f32_e32 v131, v131, v141
	v_pk_fma_f32 v[142:143], v[144:145], v[144:145], v[142:143]
	s_waitcnt vmcnt(1)
	v_mov_b32_e32 v144, v69
	v_add_f32_e32 v131, v131, v142
	s_waitcnt vmcnt(0)
	v_mov_b32_e32 v145, v65
	v_add_f32_e32 v131, v131, v143
	v_mov_b32_e32 v142, v68
	v_mov_b32_e32 v143, v64
	v_pk_mul_f32 v[144:145], v[144:145], v[144:145]
	s_mov_b32 s9, 0x10900000
	v_pk_fma_f32 v[142:143], v[142:143], v[142:143], v[144:145]
	v_mov_b32_e32 v144, v70
	v_mov_b32_e32 v145, v66
	v_pk_fma_f32 v[142:143], v[144:145], v[144:145], v[142:143]
	v_mov_b32_e32 v144, v71
	v_mov_b32_e32 v145, v67
	v_pk_fma_f32 v[142:143], v[144:145], v[144:145], v[142:143]
	v_lshl_add_u64 v[144:145], s[86:87], 0, v[134:135]
	v_add_f32_e32 v131, v131, v142
	v_add_f32_e32 v131, v131, v143
	ds_bpermute_b32 v141, v97, v131
	v_add_u32_e32 v130, s8, v130
	v_lshl_add_u64 v[132:133], v[132:133], 0, s[10:11]
	v_lshl_add_u64 v[134:135], v[134:135], 0, s[12:13]
	s_waitcnt lgkmcnt(0)
	v_add_f32_e32 v131, v131, v141
	ds_bpermute_b32 v141, v136, v131
	s_waitcnt lgkmcnt(0)
	v_add_f32_e32 v131, v131, v141
	ds_bpermute_b32 v141, v137, v131
	s_waitcnt lgkmcnt(0)
	v_add_f32_e32 v131, v131, v141
	ds_bpermute_b32 v141, v138, v131
	s_waitcnt lgkmcnt(0)
	v_add_f32_e32 v131, v131, v141
	ds_bpermute_b32 v141, v139, v131
	s_waitcnt lgkmcnt(0)
	v_add_f32_e32 v131, v131, v141
	ds_bpermute_b32 v141, v140, v131
	s_waitcnt lgkmcnt(0)
; __device__ __forceinline__ void rmsnorm_rows(const float* __restrict__ xin, const float* __restrict__ g, u16* outb, float* outf,
;                                              int row_begin, int row_end, int row_step, const int tidx) {
;     ...
;     float rs = rsqrtf(ss * (1.f / DM) + 1e-6f);
; #pragma unroll
;     for (int i = 0; i < 16; ++i) {
;       f32x4 o = v[i] * rs * ggv[i];
;       if (outb) {
;         u32x2 pk;
;         pk.x = pack2(o[0], o[1]);
;         pk.y = pack2(o[2], o[3]);
;         *reinterpret_cast<u32x2*>(outb + (size_t)row * DM + i * 256 + lane * 4) = pk;
;       } else {
;         *reinterpret_cast<f32x4*>(outf + (size_t)row * DM + i * 256 + lane * 4) = o;
;       }
;     }
	v_add_f32_e32 v131, v131, v141
	v_fmamk_f32 v131, v131, 0x39800000, v211
	v_cmp_gt_f32_e32 vcc, s1, v131
	v_mul_f32_e32 v141, 0x4b800000, v131
	s_nop 0
	v_cndmask_b32_e32 v131, v131, v141, vcc
	v_rsq_f32_e32 v131, v131
	s_nop 0
	v_mul_f32_e32 v141, 0x45800000, v131
	v_cndmask_b32_e32 v142, v131, v141, vcc
	v_pk_mul_f32 v[126:127], v[126:127], v[142:143] op_sel_hi:[1,0]
	v_pk_mul_f32 v[128:129], v[128:129], v[142:143] op_sel_hi:[1,0]
	v_pk_mul_f32 v[126:127], v[8:9], v[126:127]
	v_pk_mul_f32 v[128:129], v[10:11], v[128:129]
	v_cvt_pk_bf16_f32 v126, v126, v127
	v_pk_mul_f32 v[110:111], v[110:111], v[142:143] op_sel_hi:[1,0]
	v_cvt_pk_bf16_f32 v127, v128, v129
	v_add_co_u32_e32 v128, vcc, s9, v144
	s_mov_b32 s9, 0x10901000
	s_nop 0
	v_addc_co_u32_e32 v129, vcc, 0, v145, vcc
	v_pk_mul_f32 v[92:93], v[92:93], v[142:143] op_sel_hi:[1,0]
	v_pk_mul_f32 v[76:77], v[76:77], v[142:143] op_sel_hi:[1,0]
	v_add_co_u32_e32 v144, vcc, s9, v144
	v_pk_mul_f32 v[112:113], v[112:113], v[142:143] op_sel_hi:[1,0]
	v_pk_mul_f32 v[110:111], v[12:13], v[110:111]
	v_pk_mul_f32 v[94:95], v[94:95], v[142:143] op_sel_hi:[1,0]
	v_pk_mul_f32 v[92:93], v[28:29], v[92:93]
	v_pk_mul_f32 v[78:79], v[78:79], v[142:143] op_sel_hi:[1,0]
	v_pk_mul_f32 v[76:77], v[44:45], v[76:77]
	v_addc_co_u32_e32 v145, vcc, 0, v145, vcc
	v_pk_mul_f32 v[112:113], v[14:15], v[112:113]
	v_cvt_pk_bf16_f32 v110, v110, v111
	v_pk_mul_f32 v[94:95], v[30:31], v[94:95]
	v_cvt_pk_bf16_f32 v111, v112, v113
	v_cvt_pk_bf16_f32 v92, v92, v93
	v_pk_mul_f32 v[78:79], v[46:47], v[78:79]
	v_cvt_pk_bf16_f32 v93, v94, v95
	v_cvt_pk_bf16_f32 v76, v76, v77
	v_pk_mul_f32 v[122:123], v[122:123], v[142:143] op_sel_hi:[1,0]
	v_cvt_pk_bf16_f32 v77, v78, v79
	v_pk_mul_f32 v[118:119], v[118:119], v[142:143] op_sel_hi:[1,0]
	global_store_dwordx2 v[128:129], v[110:111], off offset:1536
	v_pk_mul_f32 v[110:111], v[114:115], v[142:143] op_sel_hi:[1,0]
	v_pk_mul_f32 v[106:107], v[106:107], v[142:143] op_sel_hi:[1,0]
	v_pk_mul_f32 v[102:103], v[102:103], v[142:143] op_sel_hi:[1,0]
	global_store_dwordx2 v[128:129], v[92:93], off offset:3584
	v_pk_mul_f32 v[92:93], v[98:99], v[142:143] op_sel_hi:[1,0]
	v_pk_mul_f32 v[88:89], v[88:89], v[142:143] op_sel_hi:[1,0]
	v_pk_mul_f32 v[84:85], v[84:85], v[142:143] op_sel_hi:[1,0]
	global_store_dwordx2 v[144:145], v[76:77], off offset:1536
	v_pk_mul_f32 v[76:77], v[80:81], v[142:143] op_sel_hi:[1,0]
	v_pk_mul_f32 v[72:73], v[72:73], v[142:143] op_sel_hi:[1,0]
	v_pk_mul_f32 v[68:69], v[68:69], v[142:143] op_sel_hi:[1,0]
	v_pk_mul_f32 v[64:65], v[64:65], v[142:143] op_sel_hi:[1,0]
	v_cmp_lt_i32_e32 vcc, s16, v130
	v_pk_mul_f32 v[124:125], v[124:125], v[142:143] op_sel_hi:[1,0]
	v_pk_mul_f32 v[122:123], v[0:1], v[122:123]
	v_pk_mul_f32 v[120:121], v[120:121], v[142:143] op_sel_hi:[1,0]
	v_pk_mul_f32 v[118:119], v[4:5], v[118:119]
	v_pk_mul_f32 v[112:113], v[116:117], v[142:143] op_sel_hi:[1,0]
	v_pk_mul_f32 v[110:111], v[16:17], v[110:111]
	v_pk_mul_f32 v[108:109], v[108:109], v[142:143] op_sel_hi:[1,0]
	v_pk_mul_f32 v[106:107], v[20:21], v[106:107]
	v_pk_mul_f32 v[104:105], v[104:105], v[142:143] op_sel_hi:[1,0]
	v_pk_mul_f32 v[102:103], v[24:25], v[102:103]
	v_pk_mul_f32 v[94:95], v[100:101], v[142:143] op_sel_hi:[1,0]
	v_pk_mul_f32 v[92:93], v[32:33], v[92:93]
	v_pk_mul_f32 v[90:91], v[90:91], v[142:143] op_sel_hi:[1,0]
	v_pk_mul_f32 v[88:89], v[36:37], v[88:89]
	v_pk_mul_f32 v[86:87], v[86:87], v[142:143] op_sel_hi:[1,0]
	v_pk_mul_f32 v[84:85], v[40:41], v[84:85]
	v_pk_mul_f32 v[78:79], v[82:83], v[142:143] op_sel_hi:[1,0]
	v_pk_mul_f32 v[76:77], v[48:49], v[76:77]
	v_pk_mul_f32 v[74:75], v[74:75], v[142:143] op_sel_hi:[1,0]
	v_pk_mul_f32 v[72:73], v[52:53], v[72:73]
	v_pk_mul_f32 v[70:71], v[70:71], v[142:143] op_sel_hi:[1,0]
	v_pk_mul_f32 v[68:69], v[56:57], v[68:69]
	v_pk_mul_f32 v[66:67], v[66:67], v[142:143] op_sel_hi:[1,0]
	v_pk_mul_f32 v[64:65], v[60:61], v[64:65]
	s_or_b64 s[14:15], vcc, s[14:15]
	global_store_dwordx2 v[144:145], v[126:127], off offset:-4096
	v_pk_mul_f32 v[124:125], v[2:3], v[124:125]
	v_cvt_pk_bf16_f32 v122, v122, v123
	v_pk_mul_f32 v[120:121], v[6:7], v[120:121]
	v_cvt_pk_bf16_f32 v123, v124, v125
	global_store_dwordx2 v[128:129], v[122:123], off offset:512
	v_cvt_pk_bf16_f32 v118, v118, v119
	v_cvt_pk_bf16_f32 v119, v120, v121
	global_store_dwordx2 v[128:129], v[118:119], off offset:1024
	v_pk_mul_f32 v[112:113], v[18:19], v[112:113]
	v_cvt_pk_bf16_f32 v110, v110, v111
	v_pk_mul_f32 v[108:109], v[22:23], v[108:109]
	v_cvt_pk_bf16_f32 v111, v112, v113
	global_store_dwordx2 v[128:129], v[110:111], off offset:2048
	v_cvt_pk_bf16_f32 v106, v106, v107
	v_cvt_pk_bf16_f32 v107, v108, v109
	global_store_dwordx2 v[128:129], v[106:107], off offset:2560
	v_pk_mul_f32 v[104:105], v[26:27], v[104:105]
	v_cvt_pk_bf16_f32 v102, v102, v103
	v_pk_mul_f32 v[94:95], v[34:35], v[94:95]
	v_cvt_pk_bf16_f32 v103, v104, v105
	global_store_dwordx2 v[128:129], v[102:103], off offset:3072
	v_cvt_pk_bf16_f32 v92, v92, v93
	v_cvt_pk_bf16_f32 v93, v94, v95
	global_store_dwordx2 v[144:145], v[92:93], off
	v_pk_mul_f32 v[90:91], v[38:39], v[90:91]
	v_cvt_pk_bf16_f32 v88, v88, v89
	v_pk_mul_f32 v[86:87], v[42:43], v[86:87]
	v_cvt_pk_bf16_f32 v89, v90, v91
	global_store_dwordx2 v[144:145], v[88:89], off offset:512
	v_cvt_pk_bf16_f32 v84, v84, v85
	v_cvt_pk_bf16_f32 v85, v86, v87
	global_store_dwordx2 v[144:145], v[84:85], off offset:1024
	v_pk_mul_f32 v[78:79], v[50:51], v[78:79]
	v_cvt_pk_bf16_f32 v76, v76, v77
	v_pk_mul_f32 v[74:75], v[54:55], v[74:75]
	v_cvt_pk_bf16_f32 v77, v78, v79
	global_store_dwordx2 v[144:145], v[76:77], off offset:2048
	v_cvt_pk_bf16_f32 v72, v72, v73
	v_cvt_pk_bf16_f32 v73, v74, v75
	global_store_dwordx2 v[144:145], v[72:73], off offset:2560
	v_pk_mul_f32 v[70:71], v[58:59], v[70:71]
	v_cvt_pk_bf16_f32 v68, v68, v69
	v_pk_mul_f32 v[66:67], v[62:63], v[66:67]
	v_cvt_pk_bf16_f32 v69, v70, v71
	global_store_dwordx2 v[144:145], v[68:69], off offset:3072
	v_cvt_pk_bf16_f32 v64, v64, v65
	v_cvt_pk_bf16_f32 v65, v66, v67
	global_store_dwordx2 v[144:145], v[64:65], off offset:3584
	s_andn2_b64 exec, exec, s[14:15]
	s_cbranch_execnz .LBB0_229
